# attention QK: negm used directly as C operand (removed 8 v_mov_b64 per tile), removed +0 adds in row-sum
# speedup vs baseline: 1.0028x; 1.0028x over previous
.LBB0_292:
	s_add_i32 s25, s2, s3
	v_cmp_ge_i32_e32 vcc, s25, v148
	v_cmp_le_i32_e64 s[0:1], s25, v149
	s_and_b32 s26, s3, 1
	s_and_b64 s[0:1], vcc, s[0:1]
	s_waitcnt lgkmcnt(0)
	s_barrier
	s_and_saveexec_b64 s[6:7], s[0:1]
	s_cbranch_execz .LBB0_300
	s_mul_i32 s0, s26, 0x5400
	v_add_u32_e32 v54, s0, v127
	v_add3_u32 v55, v54, v150, v128
	ds_read_b128 v[50:53], v55
	ds_read_b128 v[114:117], v55 offset:32
	ds_read_b128 v[118:121], v55 offset:4608
	ds_read_b128 v[136:139], v55 offset:4640
	ds_read_b128 v[140:143], v55 offset:64
	ds_read_b128 v[182:185], v55 offset:96
	ds_read_b128 v[186:189], v55 offset:4672
	ds_read_b128 v[190:193], v55 offset:4704
	v_cmp_eq_u32_e64 s[8:9], s3, v153
	v_cmp_ne_u32_e32 vcc, s3, v153
	v_add_u32_e32 v200, v54, v151
	s_setprio 1
	s_waitcnt lgkmcnt(7)
	v_mfma_f32_32x32x16_bf16 v[66:81], v[50:53], v[82:85], v[34:49]
	s_waitcnt lgkmcnt(6)
	v_mfma_f32_32x32x16_bf16 v[66:81], v[114:117], v[86:89], v[66:81]
	s_waitcnt lgkmcnt(5)
	v_mfma_f32_32x32x16_bf16 v[50:65], v[118:121], v[82:85], v[34:49]
	s_waitcnt lgkmcnt(4)
	v_mfma_f32_32x32x16_bf16 v[50:65], v[136:139], v[86:89], v[50:65]
	s_waitcnt lgkmcnt(3)
	v_mfma_f32_32x32x16_bf16 v[66:81], v[140:143], v[90:93], v[66:81]
	s_waitcnt lgkmcnt(1)
	v_mfma_f32_32x32x16_bf16 v[50:65], v[186:189], v[90:93], v[50:65]
	v_mfma_f32_32x32x16_bf16 v[66:81], v[182:185], v[94:97], v[66:81]
	v_add_u32_e32 v182, v200, v152
	s_waitcnt lgkmcnt(0)
	v_mfma_f32_32x32x16_bf16 v[50:65], v[190:193], v[94:97], v[50:65]
	s_setprio 0
	ds_read_b64_tr_b16 v[118:119], v182 offset:9216
	ds_read_b64_tr_b16 v[120:121], v182 offset:10752
	ds_read_b64_tr_b16 v[116:117], v182 offset:10816
	ds_read_b64_tr_b16 v[114:115], v182 offset:9280
	v_add_u32_e32 v136, 59, v154
	v_cmp_lt_u32_e64 s[0:1], s60, v136
	s_mov_b64 s[10:11], s[8:9]
	s_nop 0
	v_cndmask_b32_e64 v136, v198, v66, s[0:1]
	s_movk_i32 s0, 0x81
	v_cmp_gt_u32_e64 s[0:1], s0, v155
	v_add_u32_e32 v66, 57, v154
	s_nop 0
	v_cndmask_b32_e64 v137, v198, v67, s[0:1]
	v_cmp_lt_u32_e64 s[0:1], s60, v66
	v_add_u32_e32 v66, 56, v154
	s_nop 0
	v_cndmask_b32_e64 v138, v198, v68, s[0:1]
	v_cmp_lt_u32_e64 s[0:1], s60, v66
	v_add_u32_e32 v66, 51, v154
	s_nop 0
	v_cndmask_b32_e64 v139, v198, v69, s[0:1]
	v_cmp_lt_u32_e64 s[0:1], s60, v66
	v_add_u32_e32 v66, 50, v154
	s_nop 0
	v_cndmask_b32_e64 v142, v198, v70, s[0:1]
	v_cmp_lt_u32_e64 s[0:1], s60, v66
	v_add_u32_e32 v66, 49, v154
	s_nop 0
	v_cndmask_b32_e64 v143, v198, v71, s[0:1]
	v_cmp_lt_u32_e64 s[0:1], s60, v66
	v_add_u32_e32 v66, 48, v154
	s_nop 0
	v_cndmask_b32_e64 v140, v198, v72, s[0:1]
	v_cmp_lt_u32_e64 s[0:1], s60, v66
	v_add_u32_e32 v66, 43, v154
	s_nop 0
	v_cndmask_b32_e64 v141, v198, v73, s[0:1]
	v_cmp_lt_u32_e64 s[0:1], s60, v66
	v_add_u32_e32 v66, 42, v154
	s_nop 0
	v_cndmask_b32_e64 v68, v198, v74, s[0:1]
	v_cmp_lt_u32_e64 s[0:1], s60, v66
	v_add_u32_e32 v66, 41, v154
	s_nop 0
	v_cndmask_b32_e64 v69, v198, v75, s[0:1]
	v_cmp_lt_u32_e64 s[0:1], s60, v66
	v_add_u32_e32 v66, 40, v154
	s_nop 0
	v_cndmask_b32_e64 v70, v198, v76, s[0:1]
	v_cmp_lt_u32_e64 s[0:1], s60, v66
	v_add_u32_e32 v66, 35, v154
	s_nop 0
	v_cndmask_b32_e64 v71, v198, v77, s[0:1]
	v_cmp_lt_u32_e64 s[0:1], s60, v66
	v_add_u32_e32 v66, 34, v154
	s_nop 0
	v_cndmask_b32_e64 v74, v198, v78, s[0:1]
	v_cmp_lt_u32_e64 s[0:1], s60, v66
	v_add_u32_e32 v66, 33, v154
	s_nop 0
	v_cndmask_b32_e64 v75, v198, v79, s[0:1]
	v_cmp_lt_u32_e64 s[0:1], s60, v66
	v_add_u32_e32 v66, 32, v154
	s_nop 0
	v_cndmask_b32_e64 v76, v198, v80, s[0:1]
	v_cmp_lt_u32_e64 s[0:1], s60, v66
	v_add_u32_e32 v66, 27, v154
	s_nop 0
	v_cndmask_b32_e64 v77, v198, v81, s[0:1]
	v_cmp_lt_u32_e64 s[0:1], s60, v66
	s_nop 1
	v_cndmask_b32_e64 v66, v198, v50, s[0:1]
	v_add_u32_e32 v50, 26, v154
	v_cmp_lt_u32_e64 s[0:1], s60, v50
	v_add_u32_e32 v50, 25, v154
	s_nop 0
	v_cndmask_b32_e64 v67, v198, v51, s[0:1]
	v_cmp_lt_u32_e64 s[0:1], s60, v50
	v_add_u32_e32 v50, 24, v154
	v_add_u32_e32 v51, 10, v154
	v_cndmask_b32_e64 v52, v198, v52, s[0:1]
	v_cmp_lt_u32_e64 s[0:1], s60, v50
	v_add_u32_e32 v50, 19, v154
	s_nop 0
	v_cndmask_b32_e64 v53, v198, v53, s[0:1]
	v_cmp_lt_u32_e64 s[0:1], s60, v50
	v_add_u32_e32 v50, 18, v154
	s_nop 0
	v_cndmask_b32_e64 v72, v198, v54, s[0:1]
	v_cmp_lt_u32_e64 s[0:1], s60, v50
	v_add_u32_e32 v50, 17, v154
	v_add_u32_e32 v54, 9, v154
	v_cndmask_b32_e64 v73, v198, v55, s[0:1]
	v_cmp_lt_u32_e64 s[0:1], s60, v50
	v_add_u32_e32 v50, 16, v154
	v_add_u32_e32 v55, 8, v154
	v_cndmask_b32_e64 v56, v198, v56, s[0:1]
	v_cmp_lt_u32_e64 s[0:1], s60, v50
	v_add_u32_e32 v50, 11, v154
	s_nop 0
	v_cndmask_b32_e64 v57, v198, v57, s[0:1]
	v_cmp_lt_u32_e64 s[0:1], s60, v50
	s_nop 1
	v_cndmask_b32_e64 v50, v198, v58, s[0:1]
	v_cmp_lt_u32_e64 s[0:1], s60, v51
	v_add_u32_e32 v58, 3, v154
	s_nop 0
	v_cndmask_b32_e64 v51, v198, v59, s[0:1]
	v_cmp_lt_u32_e64 s[0:1], s60, v54
	v_add_u32_e32 v59, 2, v154
	s_nop 0
	v_cndmask_b32_e64 v54, v198, v60, s[0:1]
	v_cmp_lt_u32_e64 s[0:1], s60, v55
	v_add_u32_e32 v60, 1, v154
	s_nop 0
	v_cndmask_b32_e64 v55, v198, v61, s[0:1]
	v_cmp_lt_u32_e64 s[0:1], s60, v58
	s_nop 1
	v_cndmask_b32_e64 v58, v198, v62, s[0:1]
	v_cmp_lt_u32_e64 s[0:1], s60, v59
	v_max3_f32 v62, v136, v66, v137
	v_max3_f32 v62, v62, v139, v53
	v_cndmask_b32_e64 v59, v198, v63, s[0:1]
	v_cmp_lt_u32_e64 s[0:1], s60, v60
	v_max_f32_e32 v63, v138, v138
	v_max3_f32 v62, v62, v143, v73
	v_cndmask_b32_e64 v60, v198, v64, s[0:1]
	v_max_f32_e32 v64, v67, v67
	v_max_f32_e32 v63, v64, v63
	v_max3_f32 v63, v63, v52, v142
	v_max3_f32 v63, v63, v72, v140
	v_max3_f32 v63, v63, v56, v68
	v_max3_f32 v62, v62, v141, v57
	v_max3_f32 v63, v63, v50, v70
	v_cmp_lt_u32_e64 s[0:1], s60, v154
	v_max3_f32 v62, v62, v69, v51
	v_max3_f32 v63, v63, v54, v74
	v_cndmask_b32_e64 v61, v198, v65, s[0:1]
	v_max3_f32 v62, v62, v71, v55
	v_max3_f32 v63, v63, v58, v76
	v_max3_f32 v62, v62, v75, v59
	v_max3_f32 v63, v63, v60, v61
	v_max3_f32 v62, v62, v77, v63
	v_mov_b32_e32 v63, v62
	s_nop 1
	v_permlane32_swap_b32_e32 v62, v63
	v_max_f32_e32 v63, v63, v63
	v_max_f32_e32 v62, v62, v62
	v_max_f32_e32 v62, v62, v63
	s_and_saveexec_b64 s[16:17], vcc
	v_cmp_lt_f32_e64 s[0:1], s61, v62
	s_cmp_lg_u64 s[0:1], 0
	s_cselect_b64 s[0:1], -1, 0
	s_andn2_b64 s[10:11], s[8:9], exec
	s_and_b64 s[0:1], s[0:1], exec
	s_or_b64 s[10:11], s[10:11], s[0:1]
	s_or_b64 exec, exec, s[16:17]
	s_and_saveexec_b64 s[0:1], s[10:11]
	s_cbranch_execz .LBB0_299
	v_max_f32_e32 v34, v62, v62
	v_max_f32_e32 v34, 0, v34
	s_and_saveexec_b64 s[10:11], vcc
	s_cbranch_execz .LBB0_298
	v_exp_f32_e64 v36, -v34
	s_nop 0
	v_mul_f32_e32 v156, v156, v36
	v_pk_mul_f32 v[32:33], v[32:33], v[36:37] op_sel_hi:[1,0]
	v_pk_mul_f32 v[30:31], v[30:31], v[36:37] op_sel_hi:[1,0]
	v_pk_mul_f32 v[28:29], v[28:29], v[36:37] op_sel_hi:[1,0]
	v_pk_mul_f32 v[26:27], v[26:27], v[36:37] op_sel_hi:[1,0]
	v_pk_mul_f32 v[24:25], v[24:25], v[36:37] op_sel_hi:[1,0]
	v_pk_mul_f32 v[22:23], v[22:23], v[36:37] op_sel_hi:[1,0]
	v_pk_mul_f32 v[20:21], v[20:21], v[36:37] op_sel_hi:[1,0]
	v_pk_mul_f32 v[18:19], v[18:19], v[36:37] op_sel_hi:[1,0]
	v_pk_mul_f32 v[16:17], v[16:17], v[36:37] op_sel_hi:[1,0]
	v_pk_mul_f32 v[14:15], v[14:15], v[36:37] op_sel_hi:[1,0]
	v_pk_mul_f32 v[12:13], v[12:13], v[36:37] op_sel_hi:[1,0]
	v_pk_mul_f32 v[10:11], v[10:11], v[36:37] op_sel_hi:[1,0]
	v_pk_mul_f32 v[8:9], v[8:9], v[36:37] op_sel_hi:[1,0]
	v_pk_mul_f32 v[6:7], v[6:7], v[36:37] op_sel_hi:[1,0]
	v_pk_mul_f32 v[4:5], v[4:5], v[36:37] op_sel_hi:[1,0]
	v_pk_mul_f32 v[2:3], v[2:3], v[36:37] op_sel_hi:[1,0]

.LBB0_666:
	v_add_f32_e32 v0, v68, v66
	v_add_f32_e32 v50, v67, v69
	v_add_f32_e32 v0, v0, v70
	v_add_f32_e32 v50, v71, v50
	v_add_f32_e32 v0, v72, v0
	v_add_f32_e32 v50, v73, v50
	v_add_f32_e32 v0, v74, v0
	v_add_f32_e32 v50, v75, v50
	v_add_f32_e32 v0, v76, v0
	v_add_f32_e32 v50, v77, v50
	v_add_f32_e32 v0, v78, v0
	v_add_f32_e32 v50, v79, v50
	v_add_f32_e32 v0, v80, v0
	v_add_f32_e32 v50, v81, v50
	v_add_f32_e32 v0, v144, v0
	v_add_f32_e32 v50, v145, v50
	v_add_f32_e32 v0, v52, v0
	v_add_f32_e32 v50, v53, v50
	v_add_f32_e32 v0, v54, v0
	v_add_f32_e32 v50, v55, v50
	v_add_f32_e32 v0, v56, v0
	v_add_f32_e32 v50, v57, v50
	v_add_f32_e32 v0, v58, v0
	v_add_f32_e32 v50, v59, v50
	v_add_f32_e32 v0, v60, v0
	v_add_f32_e32 v50, v61, v50
	v_add_f32_e32 v0, v62, v0
	v_add_f32_e32 v50, v63, v50
	v_add_f32_e32 v0, v64, v0
	v_add_f32_e32 v50, v65, v50
	s_add_u32 s0, s0, 0x40000
	v_add_f32_e32 v0, v0, v50
	s_addc_u32 s1, s1, 0
	s_add_i32 s10, s10, 1
	v_add_f32_e32 v142, v142, v0
	s_cmp_lg_u32 s0, 0x1000000
	v_lshl_add_u64 v[128:129], v[128:129], 0, s[40:41]
	s_cbranch_scc0 .LBB0_655
.LBB0_667:
	s_and_b32 s11, s10, 1
	s_mul_i32 s4, s11, 0x6400
	s_add_i32 s8, s4, 0
	v_add3_u32 v0, s8, v138, v139
	s_waitcnt lgkmcnt(0)
	s_barrier
	ds_read_b128 v[50:53], v0
	ds_read_b128 v[118:121], v0 offset:32
	ds_read_b128 v[122:125], v0 offset:6656
	ds_read_b128 v[144:147], v0 offset:6688
	ds_read_b128 v[148:151], v0 offset:64
	ds_read_b128 v[152:155], v0 offset:96
	ds_read_b128 v[182:185], v0 offset:6720
	ds_read_b128 v[186:189], v0 offset:6752
	ds_read_b128 v[190:193], v0 offset:128
	ds_read_b128 v[202:205], v0 offset:160
	ds_read_b128 v[206:209], v0 offset:6784
	ds_read_b128 v[210:213], v0 offset:6816
	s_cmp_eq_u32 s0, 0
	s_cselect_b64 s[4:5], -1, 0
	s_cmp_lg_u32 s0, 0
	v_add_u32_e32 v0, s8, v140
	s_cselect_b64 s[6:7], -1, 0
	v_add_u32_e32 v0, v0, v141
	s_setprio 1
	s_waitcnt lgkmcnt(11)
	v_mfma_f32_32x32x16_bf16 v[66:81], v[50:53], v[82:85], v[34:49]
	s_waitcnt lgkmcnt(10)
	v_mfma_f32_32x32x16_bf16 v[66:81], v[118:121], v[86:89], v[66:81]
	s_waitcnt lgkmcnt(9)
	v_mfma_f32_32x32x16_bf16 v[50:65], v[122:125], v[82:85], v[34:49]
	s_waitcnt lgkmcnt(8)
	v_mfma_f32_32x32x16_bf16 v[50:65], v[144:147], v[86:89], v[50:65]
	s_waitcnt lgkmcnt(7)
	v_mfma_f32_32x32x16_bf16 v[66:81], v[148:151], v[90:93], v[66:81]
	s_waitcnt lgkmcnt(5)
	v_mfma_f32_32x32x16_bf16 v[50:65], v[182:185], v[90:93], v[50:65]
	v_mfma_f32_32x32x16_bf16 v[66:81], v[152:155], v[94:97], v[66:81]
	s_waitcnt lgkmcnt(4)
	v_mfma_f32_32x32x16_bf16 v[50:65], v[186:189], v[94:97], v[50:65]
	s_waitcnt lgkmcnt(3)
	v_mfma_f32_32x32x16_bf16 v[66:81], v[190:193], v[98:101], v[66:81]
	s_waitcnt lgkmcnt(1)
	v_mfma_f32_32x32x16_bf16 v[50:65], v[206:209], v[98:101], v[50:65]
	v_mfma_f32_32x32x16_bf16 v[66:81], v[202:205], v[102:105], v[66:81]
	s_waitcnt lgkmcnt(0)
	v_mfma_f32_32x32x16_bf16 v[50:65], v[210:213], v[102:105], v[50:65]
	s_setprio 0
	ds_read_b64_tr_b16 v[122:123], v0 offset:13312
	ds_read_b64_tr_b16 v[124:125], v0 offset:14848
	ds_read_b64_tr_b16 v[120:121], v0 offset:14912
	ds_read_b64_tr_b16 v[118:119], v0 offset:13376
	s_nop 4
	v_max_f32_e32 v145, v68, v68
	s_nop 0
	v_max_f32_e32 v146, v51, v51
	v_max_f32_e32 v145, v146, v145
	v_max3_f32 v144, v66, v50, v67
	v_max3_f32 v145, v145, v52, v70
	v_max3_f32 v144, v144, v69, v53
	v_max3_f32 v145, v145, v54, v72
	v_max3_f32 v144, v144, v71, v55
	v_max3_f32 v145, v145, v56, v74
	v_max3_f32 v144, v144, v73, v57
	v_max3_f32 v145, v145, v58, v76
	v_max3_f32 v144, v144, v75, v59
	v_max3_f32 v145, v145, v60, v78
	v_max3_f32 v144, v144, v77, v61
	v_max3_f32 v145, v145, v62, v80
	v_max3_f32 v144, v144, v79, v63
	v_max3_f32 v145, v145, v64, v65
	v_max3_f32 v144, v144, v81, v145
	v_mov_b32_e32 v145, v144
	s_nop 1
	v_permlane32_swap_b32_e32 v144, v145
	v_max_f32_e32 v145, v145, v145
	v_max_f32_e32 v144, v144, v144
	v_max_f32_e32 v144, v144, v145
	s_and_b64 vcc, exec, s[4:5]
	s_mov_b64 s[8:9], s[4:5]
	s_cbranch_vccnz .LBB0_669
	v_cmp_lt_f32_e32 vcc, s61, v144
	s_cmp_lg_u64 vcc, 0
	s_cselect_b64 s[8:9], -1, 0

.LBB0_801:
	v_add_f32_e32 v98, v100, v98
	v_add_f32_e32 v99, v99, v101
	v_add_f32_e32 v98, v98, v102
	v_add_f32_e32 v99, v103, v99
	v_add_f32_e32 v98, v104, v98
	v_add_f32_e32 v99, v105, v99
	v_add_f32_e32 v98, v106, v98
	v_add_f32_e32 v99, v107, v99
	v_add_f32_e32 v98, v108, v98
	v_add_f32_e32 v99, v109, v99
	v_add_f32_e32 v98, v110, v98
	v_add_f32_e32 v99, v111, v99
	v_add_f32_e32 v98, v112, v98
	v_add_f32_e32 v99, v113, v99
	v_add_f32_e32 v82, v82, v98
	v_add_f32_e32 v83, v83, v99
	v_add_f32_e32 v82, v84, v82
	v_add_f32_e32 v83, v85, v83
	v_add_f32_e32 v82, v86, v82
	v_add_f32_e32 v83, v87, v83
	v_add_f32_e32 v82, v88, v82
	v_add_f32_e32 v83, v89, v83
	v_add_f32_e32 v82, v90, v82
	v_add_f32_e32 v83, v91, v83
	v_add_f32_e32 v82, v92, v82
	v_add_f32_e32 v83, v93, v83
	v_add_f32_e32 v82, v94, v82
	v_add_f32_e32 v83, v95, v83
	v_add_f32_e32 v82, v96, v82
	v_add_f32_e32 v83, v97, v83
	s_add_u32 s10, s10, 0x60000
	v_add_f32_e32 v82, v82, v83
	s_addc_u32 s11, s11, 0
	s_add_i32 s29, s29, 1
	s_cmp_lg_u32 s10, 0x1800000
	v_add_f32_e32 v0, v0, v82
	s_cbranch_scc0 .LBB0_811
.LBB0_802:
	s_and_b32 s30, s29, 1
	s_mul_i32 s12, s30, 0x7400
	s_add_i32 s12, s12, 0
	v_add3_u32 v86, s12, v208, v209
	s_waitcnt lgkmcnt(0)
	s_barrier
	ds_read_b128 v[82:85], v86
	ds_read_b128 v[142:145], v86 offset:32
	ds_read_b128 v[146:149], v86 offset:4608
	ds_read_b128 v[150:153], v86 offset:4640
	ds_read_b128 v[154:157], v86 offset:64
	ds_read_b128 v[214:217], v86 offset:96
	ds_read_b128 v[218:221], v86 offset:4672
	ds_read_b128 v[222:225], v86 offset:4704
	s_cmp_eq_u32 s10, 0
	s_cselect_b64 s[16:17], -1, 0
	s_cmp_lg_u32 s10, 0
	v_add_u32_e32 v86, s12, v210
	s_cselect_b64 s[18:19], -1, 0
	v_add_u32_e32 v213, v86, v211
	s_setprio 1
	s_waitcnt lgkmcnt(7)
	v_mfma_f32_32x32x16_bf16 v[98:113], v[82:85], v[114:117], v[66:81]
	s_waitcnt lgkmcnt(6)
	v_mfma_f32_32x32x16_bf16 v[98:113], v[142:145], v[118:121], v[98:113]
	s_waitcnt lgkmcnt(5)
	v_mfma_f32_32x32x16_bf16 v[82:97], v[146:149], v[114:117], v[66:81]
	s_waitcnt lgkmcnt(4)
	v_mfma_f32_32x32x16_bf16 v[82:97], v[150:153], v[118:121], v[82:97]
	s_waitcnt lgkmcnt(3)
	v_mfma_f32_32x32x16_bf16 v[98:113], v[154:157], v[122:125], v[98:113]
	s_waitcnt lgkmcnt(1)
	v_mfma_f32_32x32x16_bf16 v[82:97], v[218:221], v[122:125], v[82:97]
	v_mfma_f32_32x32x16_bf16 v[98:113], v[214:217], v[126:129], v[98:113]
	s_waitcnt lgkmcnt(0)
	v_mfma_f32_32x32x16_bf16 v[82:97], v[222:225], v[126:129], v[82:97]
	s_setprio 0
	ds_read_b64_tr_b16 v[154:155], v213 offset:9216
	ds_read_b64_tr_b16 v[150:151], v213 offset:9280
	ds_read_b64_tr_b16 v[146:147], v213 offset:9344
	ds_read_b64_tr_b16 v[142:143], v213 offset:9408
	ds_read_b64_tr_b16 v[156:157], v213 offset:11776
	ds_read_b64_tr_b16 v[152:153], v213 offset:11840
	ds_read_b64_tr_b16 v[148:149], v213 offset:11904
	ds_read_b64_tr_b16 v[144:145], v213 offset:11968
	s_nop 0
	v_max_f32_e32 v214, v100, v100
	s_nop 0
	v_max_f32_e32 v215, v83, v83
	v_max_f32_e32 v214, v215, v214
	v_max3_f32 v200, v98, v82, v99
	v_max3_f32 v214, v214, v84, v102
	v_max3_f32 v200, v200, v101, v85
	v_max3_f32 v214, v214, v86, v104
	v_max3_f32 v200, v200, v103, v87
	v_max3_f32 v214, v214, v88, v106
	v_max3_f32 v200, v200, v105, v89
	v_max3_f32 v214, v214, v90, v108
	v_max3_f32 v200, v200, v107, v91
	v_max3_f32 v214, v214, v92, v110
	v_max3_f32 v200, v200, v109, v93
	v_max3_f32 v214, v214, v94, v112
	v_max3_f32 v200, v200, v111, v95
	v_max3_f32 v214, v214, v96, v97
	v_max3_f32 v200, v200, v113, v214
	v_mov_b32_e32 v214, v200
	s_nop 1
	v_permlane32_swap_b32_e32 v200, v214
	v_max_f32_e32 v214, v214, v214
	v_max_f32_e32 v200, v200, v200
	v_max_f32_e32 v214, v200, v214
	s_and_b64 vcc, exec, s[16:17]
	s_mov_b64 s[20:21], s[16:17]
	s_cbranch_vccnz .LBB0_804
	v_cmp_lt_f32_e32 vcc, s61, v214
	s_cmp_lg_u64 vcc, 0
	s_cselect_b64 s[20:21], -1, 0
